# speedup vs baseline: 1.0073x; 1.0030x over previous
; #define LAS __attribute__((address_space(3)))
; __device__ __forceinline__ void attn_unit(const bf16* __restrict__ U, const bf16* __restrict__ VT, bf16* __restrict__ Y, int b, int qb, LAS float* red, int wave, int lane) {
;     const int h = wave, fr = lane & 15, fq = lane >> 4;
;     const size_t rowq = (size_t)b * SEQ + (size_t)qb * 64;
;     bf16x8 Qf[4][2];
; #pragma unroll
;     for (int qt = 0; qt < 4; ++qt)
; #pragma unroll
;         for (int ks = 0; ks < 2; ++ks) Qf[qt][ks] = *(const bf16x8*)(U + (rowq + 16 * qt + fr) * NU + 1024 + h * 64 + 32 * ks + 8 * fq);
;     f32x4 ot[4][4];
; #pragma unroll
;     for (int dt = 0; dt < 4; ++dt)
; #pragma unroll
;         for (int qt = 0; qt < 4; ++qt) ot[dt][qt] = (f32x4){0.f, 0.f, 0.f, 0.f};
;     float carry[4] = {1.f, 1.f, 1.f, 1.f};
;     const bf16* Kbase = U + ((size_t)b * SEQ + 8 * (fr >> 2) + (fr & 3)) * NU + 1536 + h * 64 + 8 * fq;
;     const bf16* Vbase = VT + ((size_t)(b * 8 + h) * 64 + fr) * SEQ + 8 * fq;
;     bf16x8 Kn[2][2], Vn[4], Kf[2][2], Vf[4];
; __global__ void __launch_bounds__(NWAVES * 64, 2) fwd_kernel(Args args) {
;     ...
;         for (int u2 = bx; u2 < BATCH * NCH / 2; u2 += G) { const int b2 = u2 / (NCH / 2), q0 = 2 * (u2 % (NCH / 2));
;             attn_unit(U, VT, Y, b2, q0, red, wave, lane); attn_unit(U, VT, Y, b2, q0 + 1, red, wave, lane); }
.LBB0_216:
.LBB0_217:
	v_and_b32_e32 v172, 15, v207
	v_mov_b32_e32 v179, 0
	v_lshlrev_b32_e32 v0, 1, v207
	v_and_b32_e32 v1, 3, v207
	v_lshlrev_b32_e32 v178, 14, v172
	v_and_or_b32 v186, v0, 24, v1
	v_lshl_add_u64 v[0:1], s[0:1], 0, v[178:179]
	v_and_b32_e32 v178, 48, v206
	v_lshl_add_u64 v[188:189], v[0:1], 0, v[178:179]
	v_mbcnt_lo_u32_b32 v0, -1, 0
	v_mbcnt_hi_u32_b32 v0, -1, v0
	v_and_b32_e32 v1, 48, v0
	v_cmp_eq_u32_e32 vcc, 48, v1
	v_readlane_b32 s2, v238, 1
	s_and_b32 s60, s2, 0xffffffc0
	v_cndmask_b32_e64 v1, 16, 0, vcc
	v_add_lshl_u32 v175, v1, v0, 2
	v_mov_b32_e32 v1, 0x80
	v_lshl_or_b32 v181, v0, 2, v1
	v_and_b32_e32 v1, 64, v0
	v_or_b32_e32 v2, v1, v172
	v_lshlrev_b32_e32 v183, 2, v2
	v_xor_b32_e32 v2, 16, v0
	v_add_u32_e32 v1, 64, v1
	s_add_i32 s10, 0, 0x20000
	v_cmp_lt_i32_e32 vcc, v2, v1
	s_lshl_b32 s0, s60, 2
	s_ashr_i32 s61, s60, 31
	v_cndmask_b32_e32 v2, v0, v2, vcc
	s_add_i32 s0, s0, s10
	v_lshlrev_b32_e32 v185, 2, v2
	v_xor_b32_e32 v2, 32, v0
	v_lshl_add_u32 v208, v206, 2, s0
	s_lshl_b64 s[0:1], s[60:61], 1
	v_cmp_lt_i32_e32 vcc, v2, v1
	s_add_u32 s0, s38, s0
	v_lshlrev_b32_e32 v176, 3, v173
	v_cndmask_b32_e32 v0, v0, v2, vcc
	v_lshlrev_b32_e32 v174, 2, v173
	s_addc_u32 s1, s39, s1
	s_mov_b32 s59, 0
	v_mov_b32_e32 v177, v179
	v_or_b32_e32 v180, 16, v172
	v_or_b32_e32 v182, 32, v172
	v_or_b32_e32 v184, 48, v206
	v_cmp_eq_u32_e64 s[2:3], 3, v173
	v_cmp_gt_u32_e64 s[4:5], 32, v206
	v_cmp_lt_u32_e64 s[6:7], v176, v172
	v_lshlrev_b32_e32 v187, 2, v0
	v_cmp_gt_u32_e64 s[8:9], 16, v206
	v_lshl_add_u32 v209, v172, 2, s10
	v_lshl_add_u64 v[190:191], s[0:1], 0, v[178:179]
	s_mov_b64 s[62:63], 0x40000
	s_mov_b64 s[64:65], 0x80000
	s_mov_b64 s[66:67], 0xc0000
	s_mov_b32 s23, 0x2f800000
	v_mov_b32_e32 v210, 0x358637bd
	s_mov_b32 s35, 0xf800000
	v_mov_b32_e32 v211, 0x260
	v_lshlrev_b32_e32 v178, 1, v174
	s_mov_b64 s[82:83], 0x8400
	s_mov_b32 s75, 0x8000
	s_mov_b64 s[84:85], 0x10400
	s_mov_b32 s97, 0x10000
	s_mov_b64 s[86:87], 0x18400
	s_mov_b32 s33, 0x18000
	s_mov_b32 s18, s96
	s_branch .LBB0_219
